# phase 7 (FFN up): second-slot workgroups (b>=256) run at priority 1 during their first two items so both co-resident workgroups finish together (the older workgroup otherwise wins arbitration and idle
# speedup vs baseline: 1.0038x; 1.0038x over previous
.LBB0_986:
	s_cmp_lt_u32 s2, 0x100
	s_cbranch_scc1 .Lpr8_go
	s_setprio 0
	s_cmpk_ge_i32 s52, 0x400
	s_cbranch_scc1 .Lpr8_go
	s_setprio 1

.LBB0_1021:
	s_setprio 0
	v_readlane_b32 s50, v238, 40
	v_readlane_b32 s51, v238, 41
